# baseline (speedup 1.0000x reference)
; template <bool MLA>
; __device__ __forceinline__ void attn_item(unsigned char* smem, const Params& p, int b, int hh, int qt) {
;     constexpr int DQK = MLA ? 192 : 64, NS = DQK / 16, CPR = DQK / 8, KROWB = CPR * 16;
;     constexpr int KBYTES = 64 * KROWB, VBYTES = 128 * 128, STGB = KBYTES + VBYTES;
;     constexpr int NKI = KBYTES / 8192;
;     unsigned char* S0 = smem;
;     const int tid = otid(), lane = tid & 63, w = tid >> 6, l31 = lane & 31, h5 = lane >> 5;
;     const int qpos = NMETA + qt * 256 + w * 32 + l31;
;     const size_t qrow = (size_t)b * L + qpos;
;     const bf16_t* qbase;
;     bf16_t* obase;
;     const bf16_t* k1; const bf16_t* k2 = nullptr; const bf16_t* vt;
;     if constexpr (MLA) {
;         bf16_t* qb = (bf16_t*)(p.ws + OFF_Q);
;         qbase = qb + qrow * 3072 + hh * 192;
;         obase = qb + qrow * 3072 + hh * 192;
;         k1 = (const bf16_t*)(p.ws + OFF_KNOPE) + (size_t)b * L * 2048 + hh * 128;
;         k2 = (const bf16_t*)(p.ws + OFF_KROPE) + (size_t)b * L * 64;
;         vt = (const bf16_t*)(p.ws + OFF_VT) + (size_t)(b * 16 + hh) * 128 * LP;
;     } else {
;         const bf16_t* qk = (const bf16_t*)(p.ws + OFF_DQK);
;         qbase = qk + qrow * 2048 + (hh >> 1) * 128 + (hh & 1) * 64;
;         obase = (bf16_t*)(p.ws + OFF_DOM) + qrow * 2048 + hh * 128;
;         k1 = qk + (size_t)b * L * 2048 + 1024 + (hh >> 1) * 128 + (hh & 1) * 64;
;         vt = (const bf16_t*)(p.ws + OFF_DVT) + (size_t)(b * 8 + (hh >> 1)) * 128 * LP;
;     }
;     bf16x8 qf[NS];
;     attn_load_q<MLA>(p, qbase, qpos, h5, qf);
;     const float c1 = (MLA ? 0.07216878364870322f : 0.125f) * LOG2E;
;     float slope2 = 0.f;
;     if constexpr (!MLA) slope2 = exp2f(-(float)((hh >> 1) + 1)) * LOG2E;
;     const bf16_t* ksrc[NKI]; int kstr[NKI];
;     const bf16_t* vsrc[2];
; #pragma unroll
;     for (int i = 0; i < NKI; ++i) {
;         const int slot = (w + 8 * i) * 64 + lane, row = slot / CPR, pc = slot - row * CPR;
;         const int cl = (pc & ~7) | ((pc & 7) ^ ((row >> 1) & 7));
;         if constexpr (MLA) {
;             if (cl < 16) { ksrc[i] = k1 + (size_t)row * 2048 + cl * 8; kstr[i] = 64 * 2048; }
;             else { ksrc[i] = k2 + (size_t)row * 64 + (cl - 16) * 8; kstr[i] = 64 * 64; }
;         } else { ksrc[i] = k1 + (size_t)row * 2048 + cl * 8; kstr[i] = 64 * 2048; }
;     }
.LBB0_852:
	s_and_b64 vcc, exec, s[0:1]
	s_cbranch_vccz .LBB0_831
	s_ashr_i32 s0, s12, 31
	s_lshr_b32 s1, s0, 28
	s_add_i32 s1, s12, s1
	s_lshr_b32 s0, s0, 24
	s_ashr_i32 s1, s1, 4
	s_add_i32 s0, s12, s0
	s_ashr_i32 s8, s0, 8
	s_lshr_b32 s0, s1, 28
	s_add_i32 s0, s1, s0
	s_and_b32 s0, s0, -16
	s_sub_i32 s9, s1, s0
	v_mov_b32_e32 v50, v166
	s_lshl_b32 s0, s1, 12
	s_lshl_b32 s1, s12, 8
	s_sub_i32 s0, s1, s0
	v_ashrrev_i32_e32 v51, 6, v50
	v_and_b32_e32 v195, 31, v50
	v_lshlrev_b32_e32 v0, 5, v51
	v_or_b32_e32 v2, s0, v195
	v_add3_u32 v10, v2, v0, 16
	v_ashrrev_i32_e32 v11, 31, v10
	v_mad_i64_i32 v[2:3], s[0:1], s8, v180, v[10:11]
	v_mov_b64_e32 v[4:5], s[24:25]
	s_movk_i32 s2, 0x1800
	v_mad_u64_u32 v[4:5], s[0:1], v2, s2, v[4:5]
	s_mul_i32 s0, s9, 0xc0
	v_bfe_u32 v147, v50, 5, 1
	v_mad_i32_i24 v5, v3, s2, v5
	s_ashr_i32 s1, s0, 31
	v_lshlrev_b32_e32 v10, 5, v10
	v_lshl_add_u64 v[150:151], s[0:1], 1, v[4:5]
	v_lshlrev_b32_e32 v0, 4, v147
	v_ashrrev_i32_e32 v11, 31, v10
	v_readlane_b32 s0, v252, 57
	v_lshl_add_u64 v[6:7], v[150:151], 0, v[0:1]
	v_lshlrev_b64 v[10:11], 2, v[10:11]
	v_readlane_b32 s1, v252, 58
	global_load_dwordx4 v[110:113], v[6:7], off
	global_load_dwordx4 v[106:109], v[6:7], off offset:32
	global_load_dwordx4 v[102:105], v[6:7], off offset:64
	global_load_dwordx4 v[98:101], v[6:7], off offset:96
	global_load_dwordx4 v[94:97], v[6:7], off offset:128
	global_load_dwordx4 v[90:93], v[6:7], off offset:160
	global_load_dwordx4 v[86:89], v[6:7], off offset:192
	global_load_dwordx4 v[82:85], v[6:7], off offset:224
	global_load_dwordx4 v[30:33], v[6:7], off offset:256
	global_load_dwordx4 v[2:5], v[6:7], off offset:288
	global_load_dwordx4 v[26:29], v[6:7], off offset:320
	s_nop 0
	global_load_dwordx4 v[6:9], v[6:7], off offset:352
	v_lshl_add_u64 v[12:13], s[0:1], 0, v[10:11]
	v_readlane_b32 s0, v252, 55
	v_readlane_b32 s1, v252, 56
	v_and_b32_e32 v0, 32, v50
	v_lshl_add_u64 v[14:15], v[12:13], 0, v[0:1]
	v_lshl_add_u64 v[10:11], s[0:1], 0, v[10:11]
	v_lshl_add_u64 v[22:23], v[10:11], 0, v[0:1]
	global_load_dwordx4 v[34:37], v[14:15], off offset:16
	global_load_dwordx4 v[42:45], v[14:15], off
	global_load_dwordx4 v[38:41], v[22:23], off offset:16
	global_load_dwordx4 v[46:49], v[22:23], off
	global_load_dwordx4 v[10:13], v[14:15], off offset:80
	global_load_dwordx4 v[18:21], v[14:15], off offset:64
	s_nop 0
	global_load_dwordx4 v[14:17], v[22:23], off offset:80
	s_nop 0
	global_load_dwordx4 v[22:25], v[22:23], off offset:64
	s_mul_i32 s1, s8, 0x1010000
	s_mul_hi_i32 s0, s8, 0x1010000
	s_add_u32 s2, s86, s1
	s_addc_u32 s3, s87, s0
	s_lshl_b32 s0, s9, 7
	s_ashr_i32 s1, s0, 31
	s_lshl_b64 s[0:1], s[0:1], 1
	s_add_u32 s0, s2, s0
	s_addc_u32 s1, s3, s1
	s_mul_i32 s2, s8, 0x80800
	v_readlane_b32 s6, v253, 13
	s_add_u32 s2, s6, s2
	s_mov_b32 s6, 0x2aaaaaab
	v_mul_hi_i32 v0, v50, s6
	v_lshrrev_b32_e32 v52, 31, v0
	v_ashrrev_i32_e32 v0, 2, v0
	v_add_u32_e32 v56, v0, v52
	s_mul_hi_i32 s3, s8, 0x80800
	v_readlane_b32 s7, v253, 14
	s_movk_i32 s6, 0xffe8
	v_lshrrev_b32_e32 v0, 1, v56
	s_addc_u32 s3, s7, s3
	v_mad_u64_u32 v[52:53], s[6:7], v56, s6, v[50:51]
	v_xor_b32_e32 v0, v0, v50
	v_bfi_b32 v0, -8, v52, v0
	v_cmp_lt_i32_e32 vcc, 15, v0
	v_ashrrev_i32_e32 v57, 31, v56
	v_lshlrev_b32_e32 v58, 3, v0
	s_and_saveexec_b64 s[6:7], vcc
	s_xor_b64 s[6:7], exec, s[6:7]
	v_lshlrev_b64 v[52:53], 7, v[56:57]
	v_lshl_add_u64 v[52:53], s[2:3], 0, v[52:53]
	v_add_u32_e32 v0, 0xffffff80, v58
	v_lshl_add_u64 v[52:53], v[0:1], 1, v[52:53]
	s_or_saveexec_b64 s[6:7], s[6:7]
	v_mov_b64_e32 v[54:55], 0x1000
	s_xor_b64 exec, exec, s[6:7]
	v_lshlrev_b64 v[52:53], 12, v[56:57]
	v_lshl_add_u64 v[52:53], s[0:1], 0, v[52:53]
	v_ashrrev_i32_e32 v59, 31, v58
	v_lshl_add_u64 v[52:53], v[58:59], 1, v[52:53]
	v_mov_b64_e32 v[54:55], 0x20000
	s_or_b64 exec, exec, s[6:7]
	v_add_u32_e32 v62, 0x200, v50
	s_mov_b32 s6, 0x2aaaaaab
	v_mul_hi_i32 v0, v62, s6
	v_lshrrev_b32_e32 v55, 31, v0
	v_ashrrev_i32_e32 v0, 2, v0
	v_add_u32_e32 v60, v0, v55
	s_movk_i32 s6, 0xffe8
	v_lshrrev_b32_e32 v0, 1, v60
	v_mad_u64_u32 v[56:57], s[6:7], v60, s6, v[62:63]
	v_xor_b32_e32 v0, v0, v50
	v_bfi_b32 v0, -8, v56, v0
	v_cmp_lt_i32_e32 vcc, 15, v0
	v_ashrrev_i32_e32 v61, 31, v60
	v_lshlrev_b32_e32 v64, 3, v0
	s_and_saveexec_b64 s[6:7], vcc
	s_xor_b64 s[6:7], exec, s[6:7]
	v_lshlrev_b64 v[56:57], 7, v[60:61]
	v_lshl_add_u64 v[56:57], s[2:3], 0, v[56:57]
	v_add_u32_e32 v0, 0xffffff80, v64
	v_lshl_add_u64 v[56:57], v[0:1], 1, v[56:57]
	s_or_saveexec_b64 s[6:7], s[6:7]
	v_mov_b64_e32 v[58:59], 0x1000
	s_xor_b64 exec, exec, s[6:7]
	v_lshlrev_b64 v[56:57], 12, v[60:61]
	v_lshl_add_u64 v[56:57], s[0:1], 0, v[56:57]
	v_ashrrev_i32_e32 v65, 31, v64
	v_lshl_add_u64 v[56:57], v[64:65], 1, v[56:57]
	v_mov_b64_e32 v[58:59], 0x20000
	s_or_b64 exec, exec, s[6:7]
	v_add_u32_e32 v0, 0x400, v50
	s_mov_b32 s6, 0x2aaaaaab
	v_mul_hi_i32 v55, v0, s6
	v_lshrrev_b32_e32 v59, 31, v55
	v_ashrrev_i32_e32 v55, 2, v55
	v_add_u32_e32 v66, v55, v59
	s_movk_i32 s6, 0xffe8
	v_mad_u64_u32 v[60:61], s[6:7], v66, s6, v[0:1]
	v_lshrrev_b32_e32 v0, 1, v66
	v_xor_b32_e32 v0, v0, v50
	v_bfi_b32 v0, -8, v60, v0
	v_cmp_lt_i32_e32 vcc, 15, v0
	v_ashrrev_i32_e32 v67, 31, v66
	v_lshlrev_b32_e32 v68, 3, v0
	s_and_saveexec_b64 s[6:7], vcc
	s_xor_b64 s[6:7], exec, s[6:7]
	v_lshlrev_b64 v[60:61], 7, v[66:67]
	v_lshl_add_u64 v[60:61], s[2:3], 0, v[60:61]
	v_add_u32_e32 v0, 0xffffff80, v68
	v_lshl_add_u64 v[60:61], v[0:1], 1, v[60:61]
	s_or_saveexec_b64 s[2:3], s[6:7]
	v_mov_b64_e32 v[64:65], 0x1000
	s_xor_b64 exec, exec, s[2:3]
	v_lshlrev_b64 v[60:61], 12, v[66:67]
	v_lshl_add_u64 v[60:61], s[0:1], 0, v[60:61]
	v_ashrrev_i32_e32 v69, 31, v68
	v_lshl_add_u64 v[60:61], v[68:69], 1, v[60:61]
	v_mov_b64_e32 v[64:65], 0x20000
	s_or_b64 exec, exec, s[2:3]
	s_waitcnt vmcnt(11)
; __device__ __forceinline__ float bf2f(bf16_t h) { return __uint_as_float(((unsigned)h) << 16); }
; __device__ __forceinline__ bf16_t f2bf(float f) { return (bf16_t)(pack2(f, 0.0f) & 0xFFFFu); }
; #define ATTN_DMA(STAGE) do { unsigned char* sb_ = S0 + (STAGE) * STGB + lane * 16; \
;     _Pragma("unroll") for (int i_ = 0; i_ < NKI; ++i_) { dma16(ksrc[i_], sb_ + (w + 8 * i_) * 1024); ksrc[i_] += kstr[i_]; } \
;     _Pragma("unroll") for (int i_ = 0; i_ < 2; ++i_) { dma16(vsrc[i_], sb_ + KBYTES + (w + 8 * i_) * 1024); vsrc[i_] += 64; } } while (0)
; template <bool MLA>
; __device__ __forceinline__ void attn_load_q(const Params& p, const bf16_t* qbase, int qpos, int h5, bf16x8 (&qf)[MLA ? 12 : 4]) {
;     ...
;         for (int sp = 0; sp < 2; ++sp)
; #pragma unroll
;             for (int j = 0; j < 8; ++j) {
;                 int fi = sp * 16 + h5 * 8 + j;
;                 float x1 = bf2f((bf16_t)qf[8 + sp][j]), x2 = bf2f((bf16_t)qf[10 + sp][j]);
;                 float cs = ct[fi], sn = st[fi];
;                 qf[8 + sp][j] = (short)f2bf(x1 * cs - x2 * sn);
;                 qf[10 + sp][j] = (short)f2bf(x2 * cs + x1 * sn);
;             }
; template <bool MLA>
; __device__ __forceinline__ void attn_item(unsigned char* smem, const Params& p, int b, int hh, int qt) {
;     ...
; #pragma unroll
;     for (int i = 0; i < 2; ++i) {
;         const int slot = (w + 8 * i) * 64 + lane, d = slot >> 3, pc = slot & 7;
;         vsrc[i] = vt + (size_t)d * LP + (pc ^ ((d >> 1) & 7)) * 8;
;     }
;     ...
;     const int yz = h5 ^ ((l31 >> 1) & 7);
;     int off4[4];
; #pragma unroll
;     for (int c = 0; c < 4; ++c) off4[c] = (((2 * c) ^ yz) & 7) * 16;
;     f32x16 o[4];
; #pragma unroll
;     for (int d = 0; d < 4; ++d)
; #pragma unroll
;         for (int r = 0; r < 16; ++r) o[d][r] = 0.f;
;     float m_run = -INFINITY, lsum = 0.f;
;     const int q0w = NMETA + qt * 256 + w * 32;
;     __syncthreads();
;     ATTN_DMA(0);
;     ATTN_DMA(1);
;     if constexpr (MLA) asm volatile("s_waitcnt vmcnt(5)" ::: "memory"); else asm volatile("s_waitcnt vmcnt(3)" ::: "memory");
;     __builtin_amdgcn_s_barrier();
	v_and_b32_e32 v67, 0xffff0000, v30
	v_lshlrev_b32_e32 v66, 16, v30
	s_waitcnt vmcnt(9)
	v_and_b32_e32 v69, 0xffff0000, v26
	v_lshlrev_b32_e32 v68, 16, v26
	s_waitcnt vmcnt(4)
	v_pk_mul_f32 v[70:71], v[46:47], v[66:67]
	v_pk_mul_f32 v[46:47], v[46:47], v[68:69]
	v_pk_fma_f32 v[70:71], v[42:43], v[68:69], v[70:71]
	v_pk_fma_f32 v[42:43], v[42:43], v[66:67], v[46:47] neg_lo:[0,0,1] neg_hi:[0,0,1]
	v_lshlrev_b32_e32 v30, 16, v27
	v_cvt_pk_bf16_f32 v118, v42, v43
	v_and_b32_e32 v43, 0xffff0000, v31
	v_lshlrev_b32_e32 v42, 16, v31
	v_and_b32_e32 v31, 0xffff0000, v27
	v_pk_mul_f32 v[26:27], v[48:49], v[42:43]
	s_lshl_b32 s0, s8, 4
	v_pk_fma_f32 v[26:27], v[44:45], v[30:31], v[26:27]
	s_add_i32 s0, s0, s9
	v_cvt_pk_bf16_f32 v115, v26, v27
	v_pk_mul_f32 v[26:27], v[48:49], v[30:31]
	v_and_b32_e32 v31, 0xffff0000, v28
	v_pk_fma_f32 v[26:27], v[44:45], v[42:43], v[26:27] neg_lo:[0,0,1] neg_hi:[0,0,1]
	v_lshlrev_b32_e32 v30, 16, v28
	v_cvt_pk_bf16_f32 v119, v26, v27
	v_and_b32_e32 v27, 0xffff0000, v32
	v_lshlrev_b32_e32 v26, 16, v32
	v_pk_mul_f32 v[42:43], v[38:39], v[26:27]
	s_mul_i32 s2, s0, 0x104000
	v_pk_fma_f32 v[42:43], v[34:35], v[30:31], v[42:43]
	v_pk_mul_f32 v[30:31], v[38:39], v[30:31]
	s_mul_hi_i32 s1, s0, 0x104000
	v_pk_fma_f32 v[26:27], v[34:35], v[26:27], v[30:31] neg_lo:[0,0,1] neg_hi:[0,0,1]
	v_and_b32_e32 v31, 0xffff0000, v29
	v_cvt_pk_bf16_f32 v120, v26, v27
	v_and_b32_e32 v27, 0xffff0000, v33
	v_lshlrev_b32_e32 v26, 16, v33
	v_lshlrev_b32_e32 v30, 16, v29
	v_pk_mul_f32 v[28:29], v[40:41], v[26:27]
	s_add_u32 s2, s84, s2
	v_pk_fma_f32 v[28:29], v[36:37], v[30:31], v[28:29]
	s_addc_u32 s3, s85, s1
	v_cvt_pk_bf16_f32 v117, v28, v29
	v_pk_mul_f32 v[28:29], v[40:41], v[30:31]
	v_ashrrev_i32_e32 v0, 3, v50
	v_pk_fma_f32 v[26:27], v[36:37], v[26:27], v[28:29] neg_lo:[0,0,1] neg_hi:[0,0,1]
	v_and_b32_e32 v29, 0xffff0000, v6
	v_cvt_pk_bf16_f32 v121, v26, v27
	v_and_b32_e32 v27, 0xffff0000, v2
	v_lshlrev_b32_e32 v26, 16, v2
	v_lshlrev_b32_e32 v28, 16, v6
	s_waitcnt vmcnt(0)
	v_pk_mul_f32 v[30:31], v[22:23], v[26:27]
	v_pk_mul_f32 v[22:23], v[22:23], v[28:29]
	v_pk_fma_f32 v[30:31], v[18:19], v[28:29], v[30:31]
	v_pk_fma_f32 v[18:19], v[18:19], v[26:27], v[22:23] neg_lo:[0,0,1] neg_hi:[0,0,1]
	v_lshlrev_b32_e32 v2, 16, v7
	v_cvt_pk_bf16_f32 v126, v18, v19
	v_and_b32_e32 v19, 0xffff0000, v3
	v_lshlrev_b32_e32 v18, 16, v3
	v_and_b32_e32 v3, 0xffff0000, v7
	v_pk_mul_f32 v[6:7], v[24:25], v[18:19]
	s_movk_i32 s6, 0x2080
	v_pk_fma_f32 v[6:7], v[20:21], v[2:3], v[6:7]
	v_lshrrev_b32_e32 v34, 4, v50
	v_cvt_pk_bf16_f32 v123, v6, v7
	v_mov_b64_e32 v[6:7], s[2:3]
	v_mad_i64_i32 v[22:23], s[2:3], v0, s6, v[6:7]
	v_xor_b32_e32 v0, v34, v50
	v_lshlrev_b32_e32 v0, 4, v0
	v_ashrrev_i32_e32 v35, 3, v62
	v_and_b32_e32 v0, 0x70, v0
	v_mad_i64_i32 v[6:7], s[2:3], v35, s6, v[6:7]
	v_and_b32_e32 v55, 63, v50
	v_lshl_add_u64 v[22:23], v[22:23], 0, v[0:1]
	v_lshl_add_u64 v[6:7], v[6:7], 0, v[0:1]
	v_lshlrev_b32_e32 v0, 10, v51
	v_lshl_or_b32 v199, v55, 4, v0
	v_add_u32_e32 v28, 0x2000, v199
	v_readfirstlane_b32 s1, v199
	v_cvt_pk_bf16_f32 v122, v30, v31
	s_mov_b32 m0, s1
	v_readfirstlane_b32 s1, v28
	v_add_u32_e32 v30, 0x4000, v199
	s_barrier
; __device__ __forceinline__ float bf2f(bf16_t h) { return __uint_as_float(((unsigned)h) << 16); }
; __device__ __forceinline__ bf16_t f2bf(float f) { return (bf16_t)(pack2(f, 0.0f) & 0xFFFFu); }
; #define ATTN_DMA(STAGE) do { unsigned char* sb_ = S0 + (STAGE) * STGB + lane * 16; \
;     _Pragma("unroll") for (int i_ = 0; i_ < NKI; ++i_) { dma16(ksrc[i_], sb_ + (w + 8 * i_) * 1024); ksrc[i_] += kstr[i_]; } \
;     _Pragma("unroll") for (int i_ = 0; i_ < 2; ++i_) { dma16(vsrc[i_], sb_ + KBYTES + (w + 8 * i_) * 1024); vsrc[i_] += 64; } } while (0)
; template <bool MLA>
; __device__ __forceinline__ void attn_load_q(const Params& p, const bf16_t* qbase, int qpos, int h5, bf16x8 (&qf)[MLA ? 12 : 4]) {
;     ...
;         for (int sp = 0; sp < 2; ++sp)
; #pragma unroll
;             for (int j = 0; j < 8; ++j) {
;                 int fi = sp * 16 + h5 * 8 + j;
;                 float x1 = bf2f((bf16_t)qf[8 + sp][j]), x2 = bf2f((bf16_t)qf[10 + sp][j]);
;                 float cs = ct[fi], sn = st[fi];
;                 qf[8 + sp][j] = (short)f2bf(x1 * cs - x2 * sn);
;                 qf[10 + sp][j] = (short)f2bf(x2 * cs + x1 * sn);
;             }
; template <bool MLA>
; __device__ __forceinline__ void attn_item(unsigned char* smem, const Params& p, int b, int hh, int qt) {
;     ...
; #pragma unroll
;     for (int i = 0; i < 2; ++i) {
;         const int slot = (w + 8 * i) * 64 + lane, d = slot >> 3, pc = slot & 7;
;         vsrc[i] = vt + (size_t)d * LP + (pc ^ ((d >> 1) & 7)) * 8;
;     }
;     ...
;     const int yz = h5 ^ ((l31 >> 1) & 7);
;     int off4[4];
; #pragma unroll
;     for (int c = 0; c < 4; ++c) off4[c] = (((2 * c) ^ yz) & 7) * 16;
;     f32x16 o[4];
; #pragma unroll
;     for (int d = 0; d < 4; ++d)
; #pragma unroll
;         for (int r = 0; r < 16; ++r) o[d][r] = 0.f;
;     float m_run = -INFINITY, lsum = 0.f;
;     const int q0w = NMETA + qt * 256 + w * 32;
;     __syncthreads();
;     ATTN_DMA(0);
;     ATTN_DMA(1);
;     if constexpr (MLA) asm volatile("s_waitcnt vmcnt(5)" ::: "memory"); else asm volatile("s_waitcnt vmcnt(3)" ::: "memory");
;     __builtin_amdgcn_s_barrier();
;     ...
;     int stage = 0;
	global_load_lds_dwordx4 v[52:53], off
	s_mov_b32 m0, s1
	v_readfirstlane_b32 s1, v30
	v_add_u32_e32 v32, 0x6000, v199
	global_load_lds_dwordx4 v[56:57], off
	s_mov_b32 m0, s1
	v_readfirstlane_b32 s1, v32
	v_add_u32_e32 v36, 0x8000, v199
	global_load_lds_dwordx4 v[60:61], off
	s_mov_b32 m0, s1
	v_readfirstlane_b32 s1, v36
	v_add_u32_e32 v36, 0xa000, v199
	v_lshlrev_b32_e32 v0, 1, v54
	global_load_lds_dwordx4 v[22:23], off
	s_mov_b32 m0, s1
	v_readfirstlane_b32 s1, v36
	v_lshl_add_u64 v[26:27], v[52:53], 0, v[0:1]
	global_load_lds_dwordx4 v[6:7], off
	s_mov_b32 m0, s1
	v_lshlrev_b32_e32 v152, 1, v58
	global_load_lds_dwordx4 v[26:27], off
	v_add_u32_e32 v26, 0xc000, v199
	v_mov_b32_e32 v153, v1
	v_readfirstlane_b32 s1, v26
	v_add_u32_e32 v26, 0xe000, v199
	v_lshl_add_u64 v[28:29], v[56:57], 0, v[152:153]
	v_lshlrev_b32_e32 v154, 1, v64
	v_mov_b32_e32 v155, v1
	s_mov_b32 m0, s1
	v_readfirstlane_b32 s1, v26
	v_add_u32_e32 v26, 0x10000, v199
	v_lshl_add_u64 v[30:31], v[60:61], 0, v[154:155]
	global_load_lds_dwordx4 v[28:29], off
	s_mov_b32 m0, s1
	v_readfirstlane_b32 s1, v26
	v_add_u32_e32 v26, 0x12000, v199
	v_lshl_add_u64 v[32:33], v[22:23], 0, s[62:63]
	global_load_lds_dwordx4 v[30:31], off
	s_mov_b32 m0, s1
	v_readfirstlane_b32 s1, v26
	v_lshl_add_u64 v[6:7], v[6:7], 0, s[62:63]
	global_load_lds_dwordx4 v[32:33], off
	s_mov_b32 m0, s1
	v_pk_mul_f32 v[2:3], v[24:25], v[2:3]
	global_load_lds_dwordx4 v[6:7], off
	v_pk_fma_f32 v[2:3], v[20:21], v[18:19], v[2:3] neg_lo:[0,0,1] neg_hi:[0,0,1]
	v_and_b32_e32 v7, 0xffff0000, v8
	v_cvt_pk_bf16_f32 v127, v2, v3
	v_and_b32_e32 v3, 0xffff0000, v4
	v_lshlrev_b32_e32 v2, 16, v4
	v_lshlrev_b32_e32 v6, 16, v8
	v_pk_mul_f32 v[18:19], v[14:15], v[2:3]
	v_lshlrev_b32_e32 v4, 16, v9
	v_pk_fma_f32 v[18:19], v[10:11], v[6:7], v[18:19]
	v_pk_mul_f32 v[6:7], v[14:15], v[6:7]
	s_waitcnt vmcnt(5)
	v_cvt_pk_bf16_f32 v116, v42, v43
	v_pk_fma_f32 v[2:3], v[10:11], v[2:3], v[6:7] neg_lo:[0,0,1] neg_hi:[0,0,1]
	v_cvt_pk_bf16_f32 v124, v18, v19
	v_cvt_pk_bf16_f32 v128, v2, v3
	v_and_b32_e32 v3, 0xffff0000, v5
	v_lshlrev_b32_e32 v2, 16, v5
	v_and_b32_e32 v5, 0xffff0000, v9
	v_pk_mul_f32 v[6:7], v[16:17], v[2:3]
	v_mov_b32_e32 v8, v1
	v_pk_fma_f32 v[6:7], v[12:13], v[4:5], v[6:7]
	v_pk_mul_f32 v[4:5], v[16:17], v[4:5]
	v_mov_b32_e32 v16, v1
	v_pk_fma_f32 v[2:3], v[12:13], v[2:3], v[4:5] neg_lo:[0,0,1] neg_hi:[0,0,1]
	v_lshrrev_b32_e32 v4, 1, v50
	v_bitop3_b32 v4, v4, v147, 7 bitop3:0x6c
	v_and_b32_e32 v5, 64, v183
	v_lshlrev_b32_e32 v192, 4, v4
	v_xor_b32_e32 v4, 32, v183
	v_add_u32_e32 v5, 64, v5
	v_cmp_lt_i32_e32 vcc, v4, v5
	v_mov_b32_e32 v5, v1
	v_cvt_pk_bf16_f32 v129, v2, v3
	v_cndmask_b32_e32 v4, v183, v4, vcc
	v_lshlrev_b32_e32 v149, 2, v4
	v_lshlrev_b32_e32 v4, 2, v64
	v_mad_i64_i32 v[2:3], s[2:3], v35, s6, 0
	v_lshl_add_u64 v[158:159], v[60:61], 0, v[4:5]
	v_lshlrev_b32_e32 v4, 2, v58
	v_lshl_add_u64 v[160:161], v[56:57], 0, v[4:5]
	v_lshlrev_b32_e32 v4, 2, v54
	v_mad_i64_i32 v[2:3], s[0:1], s0, v188, v[2:3]
	v_lshl_add_u64 v[162:163], v[52:53], 0, v[4:5]
	v_bitop3_b32 v4, v34, 7, v50 bitop3:0x48
	v_readlane_b32 s0, v251, 7
	s_mov_b64 s[2:3], 0x100
	v_lshl_or_b32 v2, v4, 4, v2
	v_readlane_b32 s1, v251, 8
	v_mov_b32_e32 v17, v1
	v_cvt_pk_bf16_f32 v125, v6, v7
	v_lshl_add_u64 v[156:157], v[22:23], 0, s[2:3]
	v_lshl_add_u64 v[164:165], s[0:1], 0, v[2:3]
	v_mov_b32_e32 v2, v1
	v_mov_b32_e32 v3, v1
	v_mov_b32_e32 v4, v1
	v_mov_b32_e32 v6, v1
	v_mov_b32_e32 v7, v1
	v_mov_b32_e32 v9, v1
	v_mov_b32_e32 v10, v1
	v_mov_b32_e32 v11, v1
	v_mov_b32_e32 v12, v1
	v_mov_b32_e32 v13, v1
	v_mov_b32_e32 v14, v1
	v_mov_b32_e32 v15, v1
	v_mov_b64_e32 v[32:33], v[16:17]
	v_mov_b64_e32 v[48:49], v[16:17]
	v_mov_b64_e32 v[64:65], v[16:17]
	v_cvt_pk_bf16_f32 v114, v70, v71
	v_xor_b32_e32 v193, 32, v192
	v_xor_b32_e32 v196, 64, v192
	v_xor_b32_e32 v197, 0x60, v192
	v_mul_u32_u24_e32 v200, 0x180, v195
	v_lshlrev_b32_e32 v194, 7, v195
	s_mov_b32 s2, 0
	v_mov_b32_e32 v198, 0xff800000
	v_mov_b32_e32 v201, 0
	s_mov_b64 s[0:1], 0
	v_mov_b64_e32 v[30:31], v[14:15]
	v_mov_b64_e32 v[28:29], v[12:13]
	v_mov_b64_e32 v[26:27], v[10:11]
	v_mov_b64_e32 v[24:25], v[8:9]
	v_mov_b64_e32 v[22:23], v[6:7]
	v_mov_b64_e32 v[20:21], v[4:5]
	v_mov_b64_e32 v[18:19], v[2:3]
	v_mov_b64_e32 v[46:47], v[14:15]
	v_mov_b64_e32 v[44:45], v[12:13]
	v_mov_b64_e32 v[42:43], v[10:11]
	v_mov_b64_e32 v[40:41], v[8:9]
	v_mov_b64_e32 v[38:39], v[6:7]
	v_mov_b64_e32 v[36:37], v[4:5]
	v_mov_b64_e32 v[34:35], v[2:3]
	v_mov_b64_e32 v[62:63], v[14:15]
	v_mov_b64_e32 v[60:61], v[12:13]
	v_mov_b64_e32 v[58:59], v[10:11]
	v_mov_b64_e32 v[56:57], v[8:9]
	v_mov_b64_e32 v[54:55], v[6:7]
	v_mov_b64_e32 v[52:53], v[4:5]
	v_mov_b64_e32 v[50:51], v[2:3]
	v_readfirstlane_b32 s6, v166
	s_cmp_lt_u32 s6, 0x100
	s_cbranch_scc0 .Lmla_prio_done
	s_setprio 1
